# t4 + fused-epilogue exchange: slot loads use sc1 (L1 bypass) instead of buffer_inv sc1 + plain loads, removing the invalidate wait from wave 0's critical path
# baseline (speedup 1.0000x reference)
;     __device__ __forceinline__ bool run(const f32x4 (&v)[2][2][4][2], const Unit& u, int wr, int wc, int fr, int fq, PG8_LAS unsigned char* lds, int wid, int lane) const {
;     ...
;             __builtin_amdgcn_fence(__ATOMIC_ACQUIRE, "agent");
;             if (lane == 0) flag[0] = dead ? 1u : 0u;
.LBB0_944:
	s_waitcnt vmcnt(0)
	s_and_b64 exec, exec, s[10:11]
	v_cndmask_b32_e64 v16, 0, 1, s[26:27]
	ds_write_b32 v67, v16 offset:10240

;     __device__ __forceinline__ bool run(const f32x4 (&v)[2][2][4][2], const Unit& u, int wr, int wc, int fr, int fq, PG8_LAS unsigned char* lds, int wid, int lane) const {
;     ...
;         asm volatile("s_waitcnt vmcnt(0) lgkmcnt(0)" ::: "memory"); __builtin_amdgcn_s_barrier(); asm volatile("" ::: "memory");
;         const bool bad = flag[0] != 0u;
;         if (lane < 32) { const float* slot = xbuf + (size_t)(u.pm * BM + row) * 8;
;             const f32x4 q0 = *(const f32x4*)slot, q1 = *(const f32x4*)(slot + 4);
;             const float q = (((((((q0[0] + q0[1]) + q0[2]) + q0[3]) + q1[0]) + q1[1]) + q1[2]) + q1[3]);
;             S[row] = 1.0f / sqrtf(q * (1.0f / 2048.0f) + 1e-6f); }
.LBB0_947:
	s_waitcnt vmcnt(0) lgkmcnt(0)
	s_barrier
	ds_read_b32 v66, v67 offset:10240
	s_and_saveexec_b64 s[10:11], s[8:9]
	s_cbranch_execz .LBB0_949
	v_lshlrev_b64 v[14:15], 5, v[14:15]
	v_lshl_add_u64 v[22:23], s[24:25], 0, v[14:15]
	global_load_dwordx4 v[14:17], v[22:23], off sc1
	s_nop 0
	global_load_dwordx4 v[22:25], v[22:23], off offset:16 sc1
	s_mov_b32 s1, 0xf800000
	v_lshl_add_u32 v0, v0, 2, 0
	s_waitcnt vmcnt(1)
	v_add_f32_e32 v14, v14, v15
	v_add_f32_e32 v14, v16, v14
	v_add_f32_e32 v14, v17, v14
	s_waitcnt vmcnt(0)
	v_add_f32_e32 v14, v22, v14
	v_add_f32_e32 v14, v23, v14
	v_add_f32_e32 v14, v24, v14
	v_add_f32_e32 v14, v25, v14
	v_fmamk_f32 v14, v14, 0x3a000000, v1
	v_mul_f32_e32 v15, 0x4f800000, v14
	v_cmp_gt_f32_e32 vcc, s1, v14
	s_nop 1
	v_cndmask_b32_e32 v14, v14, v15, vcc
	v_sqrt_f32_e32 v15, v14
	s_nop 0
	v_add_u32_e32 v16, -1, v15
	v_add_u32_e32 v17, 1, v15
	v_fma_f32 v22, -v16, v15, v14
	v_fma_f32 v23, -v17, v15, v14
	v_cmp_ge_f32_e64 s[8:9], 0, v22
	s_nop 1
	v_cndmask_b32_e64 v15, v15, v16, s[8:9]
	v_cmp_lt_f32_e64 s[8:9], 0, v23
	s_nop 1
	v_cndmask_b32_e64 v15, v15, v17, s[8:9]
	v_mul_f32_e32 v16, 0x37800000, v15
	v_cndmask_b32_e32 v15, v15, v16, vcc
	v_cmp_class_f32_e32 vcc, v14, v236
	s_nop 1
	v_cndmask_b32_e32 v14, v15, v14, vcc
	v_div_scale_f32 v15, s[2:3], v14, v14, 1.0
	v_rcp_f32_e32 v16, v15
	v_div_scale_f32 v17, vcc, 1.0, v14, 1.0
	v_fma_f32 v22, -v15, v16, 1.0
	v_fmac_f32_e32 v16, v22, v16
	v_mul_f32_e32 v22, v17, v16
	v_fma_f32 v23, -v15, v22, v17
	v_fmac_f32_e32 v22, v23, v16
	v_fma_f32 v15, -v15, v22, v17
	v_div_fmas_f32 v15, v15, v16, v22
	v_div_fixup_f32 v14, v15, v14, 1.0
	ds_write_b32 v0, v14 offset:8192

;     __device__ __forceinline__ bool run(const f32x4 (&v)[2][2][4][2], const Unit& u, int wr, int wc, int fr, int fq, PG8_LAS unsigned char* lds, int wid, int lane) const {
;     ...
;             __builtin_amdgcn_fence(__ATOMIC_ACQUIRE, "agent");
;             if (lane == 0) flag[0] = dead ? 1u : 0u;
.LBB0_1428:
	s_waitcnt vmcnt(0)
	s_and_b64 exec, exec, s[10:11]
	v_cndmask_b32_e64 v66, 0, 1, s[20:21]
	ds_write_b32 v67, v66 offset:10240

;     __device__ __forceinline__ bool run(const f32x4 (&v)[2][2][4][2], const Unit& u, int wr, int wc, int fr, int fq, PG8_LAS unsigned char* lds, int wid, int lane) const {
;     ...
;         asm volatile("s_waitcnt vmcnt(0) lgkmcnt(0)" ::: "memory"); __builtin_amdgcn_s_barrier(); asm volatile("" ::: "memory");
;         const bool bad = flag[0] != 0u;
;         if (lane < 32) { const float* slot = xbuf + (size_t)(u.pm * BM + row) * 8;
;             const f32x4 q0 = *(const f32x4*)slot, q1 = *(const f32x4*)(slot + 4);
;             const float q = (((((((q0[0] + q0[1]) + q0[2]) + q0[3]) + q1[0]) + q1[1]) + q1[2]) + q1[3]);
;             S[row] = 1.0f / sqrtf(q * (1.0f / 2048.0f) + 1e-6f); }
.LBB0_1431:
	s_waitcnt vmcnt(0) lgkmcnt(0)
	s_barrier
	ds_read_b32 v66, v67 offset:10240
	s_and_saveexec_b64 s[10:11], s[6:7]
	s_cbranch_execz .LBB0_1433
	v_lshlrev_b64 v[120:121], 5, v[120:121]
	v_lshl_add_u64 v[136:137], s[14:15], 0, v[120:121]
	global_load_dwordx4 v[120:123], v[136:137], off sc1
	s_nop 0
	global_load_dwordx4 v[136:139], v[136:137], off offset:16 sc1
	s_mov_b32 s1, 0xf800000
	v_lshl_add_u32 v0, v0, 2, 0
	s_waitcnt vmcnt(1)
	v_add_f32_e32 v120, v120, v121
	v_add_f32_e32 v120, v122, v120
	v_add_f32_e32 v120, v123, v120
	s_waitcnt vmcnt(0)
	v_add_f32_e32 v120, v136, v120
	v_add_f32_e32 v120, v137, v120
	v_add_f32_e32 v120, v138, v120
	v_add_f32_e32 v120, v139, v120
	v_fmamk_f32 v120, v120, 0x3a000000, v1
	v_mul_f32_e32 v121, 0x4f800000, v120
	v_cmp_gt_f32_e32 vcc, s1, v120
	s_nop 1
	v_cndmask_b32_e32 v120, v120, v121, vcc
	v_sqrt_f32_e32 v121, v120
	s_nop 0
	v_add_u32_e32 v122, -1, v121
	v_add_u32_e32 v123, 1, v121
	v_fma_f32 v136, -v122, v121, v120
	v_fma_f32 v137, -v123, v121, v120
	v_cmp_ge_f32_e64 s[6:7], 0, v136
	s_nop 1
	v_cndmask_b32_e64 v121, v121, v122, s[6:7]
	v_cmp_lt_f32_e64 s[6:7], 0, v137
	s_nop 1
	v_cndmask_b32_e64 v121, v121, v123, s[6:7]
	v_mul_f32_e32 v122, 0x37800000, v121
	v_cndmask_b32_e32 v121, v121, v122, vcc
	v_cmp_class_f32_e32 vcc, v120, v236
	s_nop 1
	v_cndmask_b32_e32 v120, v121, v120, vcc
	v_div_scale_f32 v121, s[2:3], v120, v120, 1.0
	v_rcp_f32_e32 v122, v121
	v_div_scale_f32 v123, vcc, 1.0, v120, 1.0
	v_fma_f32 v136, -v121, v122, 1.0
	v_fmac_f32_e32 v122, v136, v122
	v_mul_f32_e32 v136, v123, v122
	v_fma_f32 v137, -v121, v136, v123
	v_fmac_f32_e32 v136, v137, v122
	v_fma_f32 v121, -v121, v136, v123
	v_div_fmas_f32 v121, v121, v122, v136
	v_div_fixup_f32 v120, v121, v120, 1.0
	ds_write_b32 v0, v120 offset:8192
